# PIN2: code placement test: 16-byte pad before the layer loop (same 8-byte phase as the final, hot loops 16 bytes later)
# speedup vs baseline: 1.0018x; 1.0018x over previous
; __global__ void __launch_bounds__(NTHREADS, 2) hymba_fwd(Args a) {
;     ...
;     for (int layer = 0; layer < 2; ++layer) {
;         const int pb = 2 + 3 * layer;
;         if (IN(pb)) {
.LBB0_163:
	s_mov_b64 s[0:1], 0
	v_writelane_b32 v254, s0, 53
	s_mov_b32 s99, 1
	s_nop 0
	v_writelane_b32 v254, s1, 54
	v_readlane_b32 s0, v255, 8
	v_readlane_b32 s1, v255, 9
	s_and_b64 vcc, exec, s[0:1]
	s_cbranch_vccnz .LBB0_552
	s_nop 0
	s_nop 0
	s_nop 0
	s_nop 0
